# mLSTM QN dot products: 12 LDS reads issued up front and the four 8-term chains interleaved instead of four serial load-wait-chain rounds (same arithmetic order)
# speedup vs baseline: 1.0023x; 1.0014x over previous
.LBB0_496:
	s_and_b64 vcc, exec, s[6:7]
	s_cbranch_vccnz .LBB0_500
	v_ashrrev_i32_e32 v66, 2, v140
	v_and_b32_e32 v80, 3, v140
	v_lshlrev_b32_e32 v67, 2, v80
	v_and_b32_e32 v81, 12, v140
	v_bfe_u32 v106, v66, 2, 2
	v_lshl_add_u32 v68, v80, 7, 0
	v_lshl_add_u32 v107, v66, 8, 0
	v_add_u32_e32 v108, 0x20e00, v68
	v_bitop3_b32 v68, v106, v67, v81 bitop3:0x36
	v_or_b32_e32 v69, 1, v67
	v_bitop3_b32 v69, v106, v69, v81 bitop3:0x36
	v_or_b32_e32 v70, 2, v67
	v_bitop3_b32 v70, v106, v70, v81 bitop3:0x36
	v_or_b32_e32 v71, 3, v67
	v_bitop3_b32 v71, v106, v71, v81 bitop3:0x36
	v_lshl_add_u32 v68, v68, 4, v107
	v_lshl_add_u32 v69, v69, 4, v107
	v_lshl_add_u32 v70, v70, 4, v107
	v_lshl_add_u32 v71, v71, 4, v107
	ds_read_b128 v[110:113], v68
	ds_read_b128 v[114:117], v69
	ds_read_b128 v[118:121], v70
	ds_read_b128 v[122:125], v71
	ds_read_b128 v[72:75], v108
	ds_read_b128 v[98:101], v108 offset:32
	ds_read_b128 v[126:129], v108 offset:64
	ds_read_b128 v[134:137], v108 offset:96
	ds_read_b128 v[76:79], v108 offset:16
	ds_read_b128 v[102:105], v108 offset:48
	ds_read_b128 v[130:133], v108 offset:80
	ds_read_b128 v[160:163], v108 offset:112
	v_cmp_eq_u32_e32 vcc, 0, v80
	s_waitcnt lgkmcnt(4)
	v_and_b32_e32 v168, 0xffff0000, v110
	v_mul_f32_e32 v164, v73, v168
	v_and_b32_e32 v169, 0xffff0000, v114
	v_mul_f32_e32 v165, v99, v169
	v_and_b32_e32 v170, 0xffff0000, v118
	v_mul_f32_e32 v166, v127, v170
	v_and_b32_e32 v171, 0xffff0000, v122
	v_mul_f32_e32 v167, v135, v171
	v_lshlrev_b32_e32 v168, 16, v110
	v_fmac_f32_e32 v164, v72, v168
	v_lshlrev_b32_e32 v169, 16, v114
	v_fmac_f32_e32 v165, v98, v169
	v_lshlrev_b32_e32 v170, 16, v118
	v_fmac_f32_e32 v166, v126, v170
	v_lshlrev_b32_e32 v171, 16, v122
	v_fmac_f32_e32 v167, v134, v171
	v_lshlrev_b32_e32 v168, 16, v111
	v_fmac_f32_e32 v164, v74, v168
	v_lshlrev_b32_e32 v169, 16, v115
	v_fmac_f32_e32 v165, v100, v169
	v_lshlrev_b32_e32 v170, 16, v119
	v_fmac_f32_e32 v166, v128, v170
	v_lshlrev_b32_e32 v171, 16, v123
	v_fmac_f32_e32 v167, v136, v171
	v_and_b32_e32 v168, 0xffff0000, v111
	v_fmac_f32_e32 v164, v75, v168
	v_and_b32_e32 v169, 0xffff0000, v115
	v_fmac_f32_e32 v165, v101, v169
	v_and_b32_e32 v170, 0xffff0000, v119
	v_fmac_f32_e32 v166, v129, v170
	v_and_b32_e32 v171, 0xffff0000, v123
	v_fmac_f32_e32 v167, v137, v171
	s_waitcnt lgkmcnt(0)
	v_lshlrev_b32_e32 v168, 16, v112
	v_fmac_f32_e32 v164, v76, v168
	v_lshlrev_b32_e32 v169, 16, v116
	v_fmac_f32_e32 v165, v102, v169
	v_lshlrev_b32_e32 v170, 16, v120
	v_fmac_f32_e32 v166, v130, v170
	v_lshlrev_b32_e32 v171, 16, v124
	v_fmac_f32_e32 v167, v160, v171
	v_and_b32_e32 v168, 0xffff0000, v112
	v_fmac_f32_e32 v164, v77, v168
	v_and_b32_e32 v169, 0xffff0000, v116
	v_fmac_f32_e32 v165, v103, v169
	v_and_b32_e32 v170, 0xffff0000, v120
	v_fmac_f32_e32 v166, v131, v170
	v_and_b32_e32 v171, 0xffff0000, v124
	v_fmac_f32_e32 v167, v161, v171
	v_lshlrev_b32_e32 v168, 16, v113
	v_fmac_f32_e32 v164, v78, v168
	v_lshlrev_b32_e32 v169, 16, v117
	v_fmac_f32_e32 v165, v104, v169
	v_lshlrev_b32_e32 v170, 16, v121
	v_fmac_f32_e32 v166, v132, v170
	v_lshlrev_b32_e32 v171, 16, v125
	v_fmac_f32_e32 v167, v162, v171
	v_and_b32_e32 v168, 0xffff0000, v113
	v_fmac_f32_e32 v164, v79, v168
	v_and_b32_e32 v169, 0xffff0000, v117
	v_fmac_f32_e32 v165, v105, v169
	v_and_b32_e32 v170, 0xffff0000, v121
	v_fmac_f32_e32 v166, v133, v170
	v_and_b32_e32 v171, 0xffff0000, v125
	v_fmac_f32_e32 v167, v163, v171
	v_add_f32_e32 v72, 0, v164
	v_add_f32_e32 v72, v72, v165
	v_add_f32_e32 v72, v72, v166
	v_add_f32_e32 v67, v72, v167
	v_mov_b32_e32 v68, v191
	s_nop 0
	v_add_f32_dpp v67, v67, v67 quad_perm:[1,0,3,2] row_mask:0xf bank_mask:0xf bound_ctrl:1
	s_nop 1
	v_mov_b32_dpp v68, v67 quad_perm:[2,3,0,1] row_mask:0xf bank_mask:0xf
	s_and_saveexec_b64 s[2:3], vcc
	v_lshl_add_u32 v66, v66, 2, 0
	v_add_f32_e32 v67, v67, v68
	v_add_u32_e32 v66, 0x20c00, v66
	ds_write_b32 v66, v67
	s_or_b64 exec, exec, s[2:3]
